# GU rstd-in-K-loop variant using dead SGPR pairs for temporaries (no s100/s101)
# speedup vs baseline: 1.0165x; 1.0113x over previous
; DI float rss_sum(const float* rss, int row) {
;     const f32x4* p = (const f32x4*)(rss + (size_t)row * 16); const f32x4 a = p[0], b = p[1], c = p[2], d = p[3];
;     return (((a.x + a.y) + (a.z + a.w)) + ((b.x + b.y) + (b.z + b.w))) + (((c.x + c.y) + (c.z + c.w)) + ((d.x + d.y) + (d.z + d.w))); }
; DI void row_rstd8(const float* rss, int row0, int lane, int fq, float (&rs)[8]) {
;     float v[2];
; #pragma unroll
;     for (int e = 0; e < 2; ++e) { const int p = 2 * fq + e; const int row = row0 + (p >> 2) * 128 + (p & 3) * 16; v[e] = 1.0f / sqrtf(rss_sum(rss, row) * (1.0f / DM) + EPS); }
; template <class Epi>
; DI void gemm_phase(LAS unsigned char* lds, const int tid, const Gemm g, const StaticOrder& S, const Epi& E) {
;     ...
;     for (;;) {
;         const bool has_next = S.next(ui + 1, nxt);
;         const char* nA = has_next ? (const char*)g.A + (size_t)nxt.pm * tstepA : cA; const char* nB = has_next ? (const char*)g.Bt + (size_t)nxt.pn * tstepB : cB;
;         for (int t = 0; t < nt; t += 2) {
;             const bool last = (t == nt - 2);
;             const char* a1 = cA + (size_t)(t + 1) * kstep;
;             const char* a2 = last ? nA : cA + (size_t)(t + 2) * kstep; const char* b2 = last ? nB : cB + (size_t)(t + 2) * kstep;
;             const char* a3 = a2 + kstep; const char* b3 = b2 + kstep;
.LBB0_666:
	v_readlane_b32 s26, v253, 49
	s_lshl_b32 s27, s49, 14
	s_nop 1
	s_add_u32 s26, s26, s27
	v_readlane_b32 s27, v253, 50
	s_nop 1
	s_addc_u32 s27, s27, 0
	s_nop 4
	global_load_dwordx4 v[228:231], v252, s[26:27]
	global_load_dwordx2 v[232:233], v252, s[26:27] offset:16
	global_load_dwordx2 v[238:239], v252, s[26:27] offset:24
	s_ashr_i32 s13, s12, 31
	s_lshl_b64 s[26:27], s[12:13], 19
	v_readlane_b32 s34, v254, 35
	v_readlane_b32 s35, v254, 36
	s_add_u32 s26, s34, s26
	s_addc_u32 s27, s35, s27
	s_and_b64 s[34:35], s[4:5], exec
	s_cselect_b32 s13, s27, s7
	s_cselect_b32 s52, s26, s6
	s_ashr_i32 s11, s10, 31
	s_lshl_b64 s[34:35], s[10:11], 19
	s_add_u32 s34, s15, s34
	s_addc_u32 s35, s24, s35
	s_and_b64 s[40:41], s[4:5], exec
	s_cselect_b32 s11, s35, s37
	s_cselect_b32 s53, s34, s36
	s_add_u32 s6, s6, 0x40080
	s_addc_u32 s7, s7, 0
	s_add_u32 s56, s36, 0x100
	v_mov_b32_e32 v2, 0
	s_addc_u32 s57, s37, 0
	s_mov_b32 s58, -2
	v_mov_b32_e32 v3, v2
	v_mov_b32_e32 v4, v2
	v_mov_b32_e32 v5, v2
	v_mov_b32_e32 v10, v2
	v_mov_b32_e32 v11, v2
	v_mov_b32_e32 v12, v2
	v_mov_b32_e32 v13, v2
	v_mov_b32_e32 v18, v2
	v_mov_b32_e32 v19, v2
	v_mov_b32_e32 v20, v2
	v_mov_b32_e32 v21, v2
	v_mov_b32_e32 v26, v2
	v_mov_b32_e32 v27, v2
	v_mov_b32_e32 v28, v2
	v_mov_b32_e32 v29, v2
	v_mov_b32_e32 v34, v2
	v_mov_b32_e32 v35, v2
	v_mov_b32_e32 v36, v2
	v_mov_b32_e32 v37, v2
	v_mov_b32_e32 v42, v2
	v_mov_b32_e32 v43, v2
	v_mov_b32_e32 v44, v2
	v_mov_b32_e32 v45, v2
	v_mov_b32_e32 v50, v2
	v_mov_b32_e32 v51, v2
	v_mov_b32_e32 v52, v2
	v_mov_b32_e32 v53, v2
	v_mov_b32_e32 v58, v2
	v_mov_b32_e32 v59, v2
	v_mov_b32_e32 v60, v2
	v_mov_b32_e32 v61, v2
	v_mov_b32_e32 v6, v2
	v_mov_b32_e32 v7, v2
	v_mov_b32_e32 v8, v2
	v_mov_b32_e32 v9, v2
	v_mov_b32_e32 v14, v2
	v_mov_b32_e32 v15, v2
	v_mov_b32_e32 v16, v2
	v_mov_b32_e32 v17, v2
	v_mov_b32_e32 v22, v2
	v_mov_b32_e32 v23, v2
	v_mov_b32_e32 v24, v2
	v_mov_b32_e32 v25, v2
	v_mov_b32_e32 v30, v2
	v_mov_b32_e32 v31, v2
	v_mov_b32_e32 v32, v2
	v_mov_b32_e32 v33, v2
	v_mov_b32_e32 v38, v2
	v_mov_b32_e32 v39, v2
	v_mov_b32_e32 v40, v2
	v_mov_b32_e32 v41, v2
	v_mov_b32_e32 v46, v2
	v_mov_b32_e32 v47, v2
	v_mov_b32_e32 v48, v2
	v_mov_b32_e32 v49, v2
	v_mov_b32_e32 v54, v2
	v_mov_b32_e32 v55, v2
	v_mov_b32_e32 v56, v2
	v_mov_b32_e32 v57, v2
	v_mov_b32_e32 v62, v2
	v_mov_b32_e32 v63, v2
	v_mov_b32_e32 v64, v2
	v_mov_b32_e32 v65, v2
	v_mov_b32_e32 v66, v2
	v_mov_b32_e32 v67, v2
	v_mov_b32_e32 v68, v2
	v_mov_b32_e32 v69, v2
	v_mov_b32_e32 v74, v2
	v_mov_b32_e32 v75, v2
	v_mov_b32_e32 v76, v2
	v_mov_b32_e32 v77, v2
	v_mov_b32_e32 v82, v2
	v_mov_b32_e32 v83, v2
	v_mov_b32_e32 v84, v2
	v_mov_b32_e32 v85, v2
	v_mov_b32_e32 v90, v2
	v_mov_b32_e32 v91, v2
	v_mov_b32_e32 v92, v2
	v_mov_b32_e32 v93, v2
	v_mov_b32_e32 v98, v2
	v_mov_b32_e32 v99, v2
	v_mov_b32_e32 v100, v2
	v_mov_b32_e32 v101, v2
	v_mov_b32_e32 v106, v2
	v_mov_b32_e32 v107, v2
	v_mov_b32_e32 v108, v2
	v_mov_b32_e32 v109, v2
	v_mov_b32_e32 v114, v2
	v_mov_b32_e32 v115, v2
	v_mov_b32_e32 v116, v2
	v_mov_b32_e32 v117, v2
	v_mov_b32_e32 v122, v2
	v_mov_b32_e32 v123, v2
	v_mov_b32_e32 v124, v2
	v_mov_b32_e32 v125, v2
	v_mov_b32_e32 v70, v2
	v_mov_b32_e32 v71, v2
	v_mov_b32_e32 v72, v2
	v_mov_b32_e32 v73, v2
	v_mov_b32_e32 v78, v2
	v_mov_b32_e32 v79, v2
	v_mov_b32_e32 v80, v2
	v_mov_b32_e32 v81, v2
	v_mov_b32_e32 v86, v2
	v_mov_b32_e32 v87, v2
	v_mov_b32_e32 v88, v2
	v_mov_b32_e32 v89, v2
	v_mov_b32_e32 v94, v2
	v_mov_b32_e32 v95, v2
	v_mov_b32_e32 v96, v2
	v_mov_b32_e32 v97, v2
	v_mov_b32_e32 v102, v2
	v_mov_b32_e32 v103, v2
	v_mov_b32_e32 v104, v2
	v_mov_b32_e32 v105, v2
	v_mov_b32_e32 v110, v2
	v_mov_b32_e32 v111, v2
	v_mov_b32_e32 v112, v2
	v_mov_b32_e32 v113, v2
	v_mov_b32_e32 v118, v2
	v_mov_b32_e32 v119, v2
	v_mov_b32_e32 v120, v2
	v_mov_b32_e32 v121, v2
	v_mov_b32_e32 v126, v2
	v_mov_b32_e32 v127, v2
	v_mov_b32_e32 v128, v2
	v_mov_b32_e32 v129, v2
.LBB0_667:
	s_cmp_eq_u32 s58, 2
	s_cbranch_scc0 .Lgu_rs_skip
	s_waitcnt vmcnt(8)
	v_add_f32_e32 v156, v228, v229
	v_add_f32_e32 v157, v230, v231
	v_add_f32_e32 v158, v232, v233
	v_add_f32_e32 v159, v238, v239
	v_add_f32_e32 v156, v156, v157
	v_add_f32_e32 v158, v158, v159
	v_add_f32_e32 v156, v156, v158
	s_nop 1
	v_mov_b32_dpp v157, v156 quad_perm:[1,0,3,2] row_mask:0xf bank_mask:0xf
	s_nop 0
	v_add_f32_e32 v156, v156, v157
	v_fmamk_f32 v156, v156, 0x3a800000, v241
	v_cmp_gt_f32_e32 vcc, s3, v156
	v_mul_f32_e32 v157, 0x4f800000, v156
	s_nop 1
	v_cndmask_b32_e32 v156, v156, v157, vcc
	v_sqrt_f32_e32 v157, v156
	s_nop 0
	v_add_u32_e32 v158, -1, v157
	v_fma_f32 v159, -v158, v157, v156
	v_cmp_ge_f32_e64 s[36:37], 0, v159
	v_add_u32_e32 v159, 1, v157
	s_nop 1
	v_cndmask_b32_e64 v158, v157, v158, s[36:37]
	v_fma_f32 v157, -v159, v157, v156
	v_cmp_lt_f32_e64 s[36:37], 0, v157
	s_nop 1
	v_cndmask_b32_e64 v157, v158, v159, s[36:37]
	v_mul_f32_e32 v158, 0x37800000, v157
	v_cndmask_b32_e32 v157, v157, v158, vcc
	v_cmp_class_f32_e32 vcc, v156, v242
	s_nop 1
	v_cndmask_b32_e32 v156, v157, v156, vcc
	v_div_scale_f32 v157, s[36:37], v156, v156, 1.0
	v_rcp_f32_e32 v158, v157
	s_nop 0
	v_fma_f32 v159, -v157, v158, 1.0
	v_fmac_f32_e32 v158, v159, v158
	v_div_scale_f32 v159, vcc, 1.0, v156, 1.0
	v_mul_f32_e32 v160, v159, v158
	v_fma_f32 v161, -v157, v160, v159
	v_fmac_f32_e32 v160, v161, v158
	v_fma_f32 v157, -v157, v160, v159
	s_nop 0
	v_div_fmas_f32 v157, v157, v158, v160
	v_div_fixup_f32 v156, v157, v156, 1.0
	ds_write_b32 v251, v156
